# O1 stagger delay 16us (4 x s_sleep 127)
# speedup vs baseline: 1.0022x; 1.0022x over previous
;   DI u16* Wt_in_o() const { return (u16*)(ws + WS_Wt_in_o); }
;   DI u16* y0b() const { return (u16*)(ws + WS_y0b); }
; __global__ void __launch_bounds__(256, 2) fwd_megakernel(Params p) {
;     ...
;   for (TileSched ts = tile_sched(128 * 16); ts.t < ts.hi; ts.t += ts.step) {
;     const int mt = ts.t >> 4, n2 = ts.t & 15;
;     gemm_tile_wide<1024>(p.y0b(), 1024, p.Wt_in_o(), 1024, mt * 128, n2 * 256, smem, [&](int half) { epi_o1(p, mt, 2 * n2 + half, (const float*)smem); });
.LBB0_923:
	s_getreg_b32 s99, hwreg(HW_REG_LDS_ALLOC, 0, 12)
	s_cmp_eq_u32 s99, 0
	s_cbranch_scc1 .Lstag_o1
	s_sleep 127
	s_sleep 127
	s_sleep 127
	s_sleep 127
